# P0: first xn-rmsnorm iteration's 16 loads issued ahead of the weight-transpose section, xn loop software-pipelined with a second register set
# speedup vs baseline: 1.0186x; 1.0046x over previous
.LBB0_5:
	s_or_b64 exec, exec, s[4:5]
	s_load_dwordx16 s[56:71], s[0:1], 0x40
	v_lshrrev_b32_e32 v32, 6, v0
	s_lshl_b32 s3, s2, 3
	v_or_b32_e32 v91, s3, v32
	v_writelane_b32 v252, s3, 0
	s_movk_i32 s3, 0x1800
	v_and_b32_e32 v165, 63, v0
	s_lshl_b32 s92, s82, 3
	v_cmp_gt_i32_e32 vcc, s3, v91
	v_and_b32_e32 v1, 31, v0
	v_lshlrev_b32_e32 v205, 3, v0
	v_and_b32_e32 v185, 3, v0
	s_load_dwordx2 s[100:101], s[0:1], 0x0
	v_lshlrev_b32_e32 v226, 14, v91
	v_lshl_or_b32 v226, v165, 4, v226
	v_mov_b32_e32 v227, 0
	s_movk_i32 s98, 0x1000
	s_mov_b32 s99, 0
	s_waitcnt lgkmcnt(0)
	v_lshl_add_u64 v[226:227], v[226:227], 0, s[100:101]
	v_lshl_add_u64 v[228:229], v[226:227], 0, s[98:99]
	v_lshl_add_u64 v[230:231], v[228:229], 0, s[98:99]
	v_lshl_add_u64 v[232:233], v[230:231], 0, s[98:99]
	global_load_dwordx4 v[222:225], v[226:227], off
	global_load_dwordx4 v[218:221], v[226:227], off offset:1024
	global_load_dwordx4 v[210:213], v[226:227], off offset:3072
	global_load_dwordx4 v[214:217], v[226:227], off offset:2048
	global_load_dwordx4 v[206:209], v[228:229], off
	global_load_dwordx4 v[158:161], v[228:229], off offset:1024
	global_load_dwordx4 v[154:157], v[228:229], off offset:2048
	global_load_dwordx4 v[150:153], v[228:229], off offset:3072
	global_load_dwordx4 v[146:149], v[230:231], off
	global_load_dwordx4 v[142:145], v[230:231], off offset:1024
	global_load_dwordx4 v[138:141], v[230:231], off offset:2048
	global_load_dwordx4 v[134:137], v[230:231], off offset:3072
	global_load_dwordx4 v[130:133], v[232:233], off
	global_load_dwordx4 v[126:129], v[232:233], off offset:1024
	global_load_dwordx4 v[122:125], v[232:233], off offset:2048
	global_load_dwordx4 v[118:121], v[232:233], off offset:3072
	s_and_saveexec_b64 s[6:7], vcc
	s_cbranch_execz .LBB0_52
	v_lshlrev_b32_e32 v2, 5, v0
	v_and_b32_e32 v14, 0x400, v2
	v_and_b32_e32 v2, 56, v205
	v_lshrrev_b32_e32 v35, 3, v165
	v_mul_u32_u24_e32 v7, 0x84, v2
	v_lshlrev_b32_e32 v2, 1, v2
	v_mov_b32_e32 v3, 0
	v_lshl_add_u32 v6, v32, 14, 0
	v_lshl_add_u64 v[10:11], s[80:81], 0, v[2:3]
	s_mov_b64 s[4:5], 0x1388800
	v_lshlrev_b32_e32 v2, 2, v35
	v_lshrrev_b32_e32 v33, 5, v165
	v_lshl_add_u64 v[4:5], v[10:11], 0, s[4:5]
	v_add3_u32 v36, v6, v7, v2
	v_bfe_i32 v2, v0, 2, 1
	s_movk_i32 s4, 0xb00
	v_lshl_add_u32 v15, v1, 2, v6
	s_movk_i32 s8, 0x84
	v_and_or_b32 v40, v2, s4, v185
	v_or_b32_e32 v2, 2, v33
	v_mov_b32_e32 v6, 0x108
	v_mad_u32_u24 v17, v2, s8, v6
	v_mov_b32_e32 v6, 0x318
	v_mad_u32_u24 v18, v2, s8, v6
	v_mov_b32_e32 v6, 0x528
	v_lshlrev_b32_e32 v12, 5, v32
	v_mad_u32_u24 v19, v2, s8, v6
	v_mov_b32_e32 v6, 0x738
	s_mov_b64 s[4:5], 0x888800
	s_waitcnt lgkmcnt(0)
	s_cmp_lg_u64 s[70:71], 0
	v_lshl_or_b32 v20, s2, 8, v12
	v_mul_u32_u24_e32 v16, 0x84, v2
	v_mad_u32_u24 v2, v2, s8, v6
	v_lshl_add_u64 v[6:7], v[10:11], 0, s[4:5]
	s_mov_b64 s[4:5], 0x688800
	s_cselect_b64 s[10:11], -1, 0
	v_add_u32_e32 v12, 0xfffff580, v20
	v_or_b32_e32 v20, v20, v1
	s_lshl_b32 s23, s2, 14
	v_or_b32_e32 v13, v14, v1
	v_mad_u32_u24 v34, v33, s8, v15
	v_lshl_add_u64 v[8:9], v[10:11], 0, s[4:5]
	s_mov_b64 s[4:5], 0x108800
	v_lshlrev_b32_e32 v41, 3, v20
	v_lshlrev_b32_e32 v42, 11, v32
	v_or_b32_e32 v14, s23, v14
	v_lshlrev_b32_e32 v20, 5, v91
	v_lshlrev_b32_e32 v21, 1, v32
	s_mov_b32 s3, 0
	v_or_b32_e32 v37, 8, v35
	v_or_b32_e32 v38, 16, v35
	v_or_b32_e32 v39, 24, v35
	v_lshl_add_u64 v[10:11], v[10:11], 0, s[4:5]
	s_mov_b64 s[8:9], 0
	s_lshl_b32 s20, s92, 5
	s_lshl_b32 s21, s92, 8
	s_lshl_b32 s22, s92, 11
	v_add_u32_e32 v43, 0xff6c0000, v14
	v_add_u32_e32 v44, 0xfffdb000, v20
	v_or_b32_e32 v45, v1, v42
	v_lshl_or_b32 v46, s2, 4, v21
	s_lshl_b32 s24, s92, 1
	v_add_u32_e32 v47, 0xffd40000, v14
	v_add_u32_e32 v48, 0xffff5000, v20
	s_movk_i32 s25, 0x57f
	s_movk_i32 s26, 0x77f
	s_movk_i32 s27, 0x127f
	s_mov_b32 s28, 0x16000
	s_mov_b32 s29, 0x2c000
	s_mov_b32 s30, 0xb000
	s_mov_b32 s31, 0x21000
	s_mov_b32 s33, 0x37000
	s_mov_b32 s34, 0x42000
	s_mov_b32 s35, 0x4d000
	s_mov_b32 s36, 0x58000
	s_mov_b32 s37, 0x63000
	s_mov_b32 s38, 0x6e000
	s_mov_b32 s39, 0x79000
	s_mov_b32 s40, 0x84000
	s_mov_b32 s41, 0x8f000
	s_mov_b32 s42, 0x9a000
	s_mov_b32 s43, 0xa5000
	s_mov_b32 s44, 0xb0000
	s_mov_b32 s45, 0xbb000
	s_mov_b32 s46, 0xc6000
	s_mov_b32 s47, 0xd1000
	s_mov_b32 s48, 0xdc000
	s_mov_b32 s49, 0xe7000
	s_mov_b32 s50, 0xf2000
	s_mov_b32 s51, 0xfd000
	s_mov_b32 s52, 0x108000
	s_mov_b32 s53, 0x113000
	s_mov_b32 s54, 0x11e000
	s_mov_b32 s55, 0x129000
	s_mov_b32 s84, 0x134000
	v_add_u32_e32 v49, v15, v17
	v_add_u32_e32 v50, v15, v19
	s_movk_i32 s85, 0xf500
	s_mov_b32 s86, 0x2e8ba2e9
	s_movk_i32 s87, 0xa80
	s_movk_i32 s88, 0xfd80
	s_movk_i32 s89, 0x2c00
	s_movk_i32 s90, 0x17ff
	v_add_u32_e32 v51, 0x400, v34
	v_add_u32_e32 v52, 0x800, v34
	v_add_u32_e32 v53, 0xc00, v34
	v_add_u32_e32 v54, 0x1000, v34
	v_add_u32_e32 v55, 0x1400, v34
	v_add_u32_e32 v56, 0x1800, v34
	v_add_u32_e32 v57, 0x1c00, v34
	v_add_u32_e32 v58, v15, v16
	v_add_u32_e32 v59, v15, v18
	v_add_u32_e32 v60, v15, v2
	v_mov_b32_e32 v61, v91
	s_branch .LBB0_8

.LBB0_52:
	s_or_b64 exec, exec, s[6:7]
	s_load_dwordx16 s[4:19], s[0:1], 0x0
	s_movk_i32 s0, 0x4080
	v_lshlrev_b32_e32 v164, 2, v165
	v_mov_b32_e32 v83, 0
	v_cmp_gt_i32_e32 vcc, s0, v91
	s_waitcnt lgkmcnt(0)
	v_writelane_b32 v252, s4, 1
	v_lshlrev_b32_e32 v162, 3, v165
	v_mbcnt_lo_u32_b32 v204, -1, 0
	v_writelane_b32 v252, s5, 2
	v_writelane_b32 v252, s6, 3
	v_writelane_b32 v252, s7, 4
	v_writelane_b32 v252, s8, 5
	v_writelane_b32 v252, s9, 6
	v_writelane_b32 v252, s10, 7
	v_writelane_b32 v252, s11, 8
	v_writelane_b32 v252, s12, 9
	v_writelane_b32 v252, s13, 10
	v_writelane_b32 v252, s14, 11
	v_writelane_b32 v252, s15, 12
	v_writelane_b32 v252, s16, 13
	v_writelane_b32 v252, s17, 14
	v_writelane_b32 v252, s18, 15
	v_writelane_b32 v252, s19, 16
	s_and_saveexec_b64 s[12:13], vcc
	s_cbranch_execz .LBB0_75
	v_lshlrev_b32_e32 v82, 2, v164
	global_load_dwordx4 v[2:5], v82, s[56:57]
	global_load_dwordx4 v[6:9], v82, s[56:57] offset:1024
	global_load_dwordx4 v[10:13], v82, s[56:57] offset:2048
	global_load_dwordx4 v[14:17], v82, s[56:57] offset:3072
	s_add_u32 s8, s80, 0x1908800
	s_addc_u32 s9, s81, 0
	v_and_b32_e32 v20, 1, v0
	v_and_b32_e32 v18, 0x1f0, v205
	v_mov_b32_e32 v19, v83
	v_cmp_eq_u32_e64 s[4:5], 0, v20
	v_lshl_add_u64 v[18:19], s[8:9], 0, v[18:19]
	v_lshlrev_b32_e32 v20, 9, v20
	v_mov_b32_e32 v21, v83
	v_lshl_add_u64 v[86:87], v[18:19], 0, v[20:21]
	v_lshlrev_b32_e32 v18, 2, v32
	v_mbcnt_hi_u32_b32 v94, -1, v204
	s_add_u32 s16, s80, 0xc3000
	v_mov_b32_e32 v163, v83
	v_lshl_or_b32 v88, s2, 5, v18
	v_and_b32_e32 v18, 64, v94
	s_mov_b32 s14, 0
	v_cmp_eq_u32_e64 s[0:1], 0, v165
	v_cmp_ne_u32_e64 s[6:7], 0, v165
	s_addc_u32 s17, s81, 0
	v_lshl_add_u64 v[84:85], s[8:9], 0, v[162:163]
	s_lshl_b32 s3, s82, 5
	s_mov_b64 s[18:19], 0
	s_movk_i32 s22, 0x4044
	s_movk_i32 s23, 0x3fff
	s_movk_i32 s24, 0x403f
	v_mov_b32_e32 v92, 0x358637bd
	s_mov_b32 s25, 0xf800000
	v_mov_b32_e32 v93, 0x260
	s_mov_b32 s26, 0x800000
	s_movk_i32 s27, 0x407f
	v_add_u32_e32 v95, 64, v18
	v_xor_b32_e32 v96, 1, v94
	v_xor_b32_e32 v97, 2, v94
	v_xor_b32_e32 v98, 4, v94
	v_xor_b32_e32 v99, 8, v94
	v_xor_b32_e32 v100, 16, v94
	s_cmpk_lg_u32 s82, 0x100
	s_cbranch_scc1 .Lxn_slow
	s_mov_b32 s100, 0x2000000
	s_mov_b32 s101, 0
	s_mov_b32 s99, 0
	s_waitcnt vmcnt(0)
	s_branch .Lxn_fcopy
